# in-projection layer 0: odd blocks run their low-rank tile before the five GEMM tiles (staggering the two XCD halves' epilogue store bursts)
# baseline (speedup 1.0000x reference)
.LBB0_218:
	s_or_b64 exec, exec, s[0:1]
	s_mov_b32 s100, 0
	s_cmpk_lt_i32 s86, 0x500
	s_cselect_b64 s[0:1], -1, 0
	v_readlane_b32 s64, v254, 12
	v_writelane_b32 v253, s0, 12
	s_cmpk_gt_i32 s86, 0x4ff
	v_readlane_b32 s68, v254, 16
	v_readlane_b32 s69, v254, 17
	s_waitcnt lgkmcnt(0)
	s_barrier
	v_writelane_b32 v253, s1, 13
	v_readlane_b32 s65, v254, 13
	v_readlane_b32 s66, v254, 14
	v_readlane_b32 s67, v254, 15
	v_readlane_b32 s70, v254, 18
	v_readlane_b32 s71, v254, 19
	v_readlane_b32 s72, v254, 20
	v_readlane_b32 s73, v254, 21
	v_readlane_b32 s74, v254, 22
	v_readlane_b32 s75, v254, 23
	v_readlane_b32 s76, v254, 24
	v_readlane_b32 s77, v254, 25
	v_readlane_b32 s78, v254, 26
	v_readlane_b32 s79, v254, 27
	s_cbranch_scc1 .LBB0_227
	s_bitcmp1_b32 s86, 0
	s_cbranch_scc0 .Lgi0_tiles
	s_cmp_eq_u32 s100, 0
	s_cbranch_scc0 .Lgi0_tiles
	s_mov_b32 s100, 1
	s_branch .LBB0_227
.Lgi0_tiles:
	s_add_i32 s33, 0, 0x10000
	s_add_i32 s80, 0, 0x14000
	s_mov_b64 s[6:7], 0x80
	s_add_i32 s81, 0, 0x18000
	s_add_i32 s82, 0, 0x1c000
	s_mov_b64 s[2:3], 0x100080
	s_mov_b64 s[8:9], 0x100
	s_mov_b64 s[10:11], 0x100100
	s_mov_b64 s[12:13], 0x180
	s_mov_b64 s[14:15], 0x100180
	v_mbcnt_hi_u32_b32 v144, -1, v181
	s_movk_i32 s83, 0x5040
	v_mov_b32_e32 v145, 1
	s_mov_b32 s87, s86
	s_waitcnt vmcnt(0)
	s_branch .LBB0_221

.LBB0_227:
	s_waitcnt vmcnt(0)
	s_cmp_eq_u32 s100, 2
	s_cbranch_scc1 .LBB0_233
	v_cndmask_b32_e64 v0, 0, 1, s[4:5]
	v_cmp_ne_u32_e64 s[0:1], 1, v0
	s_andn2_b64 vcc, exec, s[4:5]
	s_nop 0
	v_writelane_b32 v253, s0, 14
	s_nop 1
	v_writelane_b32 v253, s1, 15
	s_cbranch_vccnz .LBB0_233
	v_mov_b32_e32 v1, 0
	s_mov_b32 s6, s86
	s_branch .LBB0_230

.LBB0_233:
	s_cmp_eq_u32 s100, 1
	s_cbranch_scc0 .Lgi0_end
	s_mov_b32 s100, 2
	v_readlane_b32 s68, v254, 16
	v_readlane_b32 s69, v254, 17
	s_branch .Lgi0_tiles

	.amdhsa_kernel _Z11mega_kernel6Params
		.amdhsa_group_segment_fixed_size 0
		.amdhsa_private_segment_fixed_size 0
		.amdhsa_kernarg_size 672
		.amdhsa_user_sgpr_count 2
		.amdhsa_user_sgpr_dispatch_ptr 0
		.amdhsa_user_sgpr_queue_ptr 0
		.amdhsa_user_sgpr_kernarg_segment_ptr 1
		.amdhsa_user_sgpr_dispatch_id 0
		.amdhsa_user_sgpr_kernarg_preload_length 0
		.amdhsa_user_sgpr_kernarg_preload_offset 0
		.amdhsa_user_sgpr_private_segment_size 0
		.amdhsa_uses_dynamic_stack 0
		.amdhsa_enable_private_segment 0
		.amdhsa_system_sgpr_workgroup_id_x 1
		.amdhsa_system_sgpr_workgroup_id_y 0
		.amdhsa_system_sgpr_workgroup_id_z 0
		.amdhsa_system_sgpr_workgroup_info 0
		.amdhsa_system_vgpr_workitem_id 2
		.amdhsa_next_free_vgpr 255
		.amdhsa_next_free_sgpr 101
		.amdhsa_accum_offset 256
		.amdhsa_reserve_vcc 1
		.amdhsa_float_round_mode_32 0
		.amdhsa_float_round_mode_16_64 0
		.amdhsa_float_denorm_mode_32 3
		.amdhsa_float_denorm_mode_16_64 3
		.amdhsa_dx10_clamp 1
		.amdhsa_ieee_mode 1
		.amdhsa_fp16_overflow 0
		.amdhsa_tg_split 0
		.amdhsa_exception_fp_ieee_invalid_op 0
		.amdhsa_exception_fp_denorm_src 0
		.amdhsa_exception_fp_ieee_div_zero 0
		.amdhsa_exception_fp_ieee_overflow 0
		.amdhsa_exception_fp_ieee_underflow 0
		.amdhsa_exception_fp_ieee_inexact 0
		.amdhsa_exception_int_div_zero 0
	.end_amdhsa_kernel

.Lfunc_end0:
	.size	_Z11mega_kernel6Params, .Lfunc_end0-_Z11mega_kernel6Params
	.set _Z11mega_kernel6Params.num_vgpr, 255
	.set _Z11mega_kernel6Params.num_agpr, 0
	.set _Z11mega_kernel6Params.numbered_sgpr, 101
	.set _Z11mega_kernel6Params.num_named_barrier, 0
	.set _Z11mega_kernel6Params.private_seg_size, 0
	.set _Z11mega_kernel6Params.uses_vcc, 1
	.set _Z11mega_kernel6Params.uses_flat_scratch, 0
	.set _Z11mega_kernel6Params.has_dyn_sized_stack, 0
	.set _Z11mega_kernel6Params.has_recursion, 0
	.set _Z11mega_kernel6Params.has_indirect_call, 0

amdhsa.kernels:
  - .agpr_count:     0
    .args:
      - .offset:         0
        .size:           416
        .value_kind:     by_value
      - .offset:         416
        .size:           4
        .value_kind:     hidden_block_count_x
      - .offset:         420
        .size:           4
        .value_kind:     hidden_block_count_y
      - .offset:         424
        .size:           4
        .value_kind:     hidden_block_count_z
      - .offset:         428
        .size:           2
        .value_kind:     hidden_group_size_x
      - .offset:         430
        .size:           2
        .value_kind:     hidden_group_size_y
      - .offset:         432
        .size:           2
        .value_kind:     hidden_group_size_z
      - .offset:         434
        .size:           2
        .value_kind:     hidden_remainder_x
      - .offset:         436
        .size:           2
        .value_kind:     hidden_remainder_y
      - .offset:         438
        .size:           2
        .value_kind:     hidden_remainder_z
      - .offset:         456
        .size:           8
        .value_kind:     hidden_global_offset_x
      - .offset:         464
        .size:           8
        .value_kind:     hidden_global_offset_y
      - .offset:         472
        .size:           8
        .value_kind:     hidden_global_offset_z
      - .offset:         480
        .size:           2
        .value_kind:     hidden_grid_dims
      - .offset:         504
        .size:           8
        .value_kind:     hidden_multigrid_sync_arg
      - .offset:         536
        .size:           4
        .value_kind:     hidden_dynamic_lds_size
    .group_segment_fixed_size: 0
    .kernarg_segment_align: 8
    .kernarg_segment_size: 672
    .language:       OpenCL C
    .language_version:
      - 2
      - 0
    .max_flat_workgroup_size: 512
    .name:           _Z11mega_kernel6Params
    .private_segment_fixed_size: 0
    .sgpr_count:     107
    .sgpr_spill_count: 102
    .symbol:         _Z11mega_kernel6Params.kd
    .uniform_work_group_size: 1
    .uses_dynamic_stack: false
    .vgpr_count:     255
    .vgpr_spill_count: 0
    .wavefront_size: 64
